# GEMM prologue: K-tile 1 half-tiles issued together with K-tile 0 (14 LDS-DMA up front, first wait vmcnt(8))
# baseline (speedup 1.0000x reference)
.LBB0_320:
	s_andn2_b64 vcc, exec, s[0:1]
	s_cbranch_vccnz .LBB0_399
	v_bfe_i32 v2, v12, 27, 1
	v_lshlrev_b32_e32 v0, 4, v12
	v_lshrrev_b32_e32 v2, 22, v2
	v_add_u32_e32 v2, v0, v2
	v_and_b32_e32 v2, 0xfffffc00, v2
	v_sub_u32_e32 v2, v0, v2
	v_ashrrev_i32_e32 v1, 31, v12
	s_waitcnt lgkmcnt(0)
	v_lshrrev_b32_e32 v3, 4, v2
	v_lshrrev_b32_e32 v1, 26, v1
	v_bitop3_b32 v2, v3, v2, 32 bitop3:0x6c
	v_add_u32_e32 v1, v12, v1
	v_ashrrev_i32_e32 v4, 31, v2
	v_ashrrev_i32_e32 v1, 6, v1
	v_lshrrev_b32_e32 v4, 26, v4
	v_lshlrev_b32_e32 v3, 3, v1
	v_add_u32_e32 v4, v2, v4
	v_and_b32_e32 v3, -16, v3
	v_ashrrev_i32_e32 v5, 6, v4
	v_lshlrev_b32_e32 v1, 5, v1
	v_add_u32_e32 v3, v5, v3
	v_and_b32_e32 v13, 32, v1
	v_and_b32_e32 v1, 0xc0, v4
	v_sub_u32_e32 v1, v2, v1
	v_lshlrev_b32_e32 v2, 1, v3
	v_lshrrev_b32_e32 v4, 2, v3
	v_and_b32_e32 v5, 3, v5
	s_mov_b32 s1, 0x7fffffe0
	v_ashrrev_i16_sdwa v1, v155, sext(v1) dst_sel:DWORD dst_unused:UNUSED_PAD src0_sel:DWORD src1_sel:BYTE_0
	v_and_b32_e32 v2, 24, v2
	v_and_b32_e32 v4, 4, v4
	v_and_or_b32 v5, v3, s1, v5
	v_bfe_i32 v14, v1, 0, 16
	v_or3_b32 v2, v5, v4, v2
	v_readlane_b32 s52, v233, 50
	v_add_u32_e32 v1, v13, v14
	v_add_u32_e32 v0, 0x2000, v0
	v_mul_lo_u32 v15, v3, s52
	v_mul_lo_u32 v2, v2, s52
	v_add_lshl_u32 v130, v1, v15, 1
	v_add_lshl_u32 v96, v2, v1, 1
	v_ashrrev_i32_e32 v1, 31, v0
	v_lshrrev_b32_e32 v1, 22, v1
	v_add_u32_e32 v1, v0, v1
	v_ashrrev_i32_e32 v1, 10, v1
	v_readlane_b32 s53, v233, 51
	v_mul_i32_i24_e32 v2, 0x400, v1
	v_sub_u32_e32 v0, v0, v2
	s_mov_b32 s53, s47
	v_lshrrev_b32_e32 v2, 4, v0
	s_lshl_b64 s[72:73], s[52:53], 9
	s_ashr_i32 s9, s46, 31
	v_bitop3_b32 v0, v2, v0, 32 bitop3:0x6c
	s_mul_i32 s9, s72, s9
	s_mul_hi_u32 s39, s72, s46
	v_ashrrev_i32_e32 v3, 31, v0
	s_add_i32 s9, s39, s9
	s_lshr_b32 s39, s52, 23
	v_writelane_b32 v232, s76, 22
	v_lshrrev_b32_e32 v3, 26, v3
	s_mul_i32 s40, s39, s46
	v_writelane_b32 v232, s77, 23
	v_lshlrev_b32_e32 v2, 3, v1
	v_add_u32_e32 v3, v0, v3
	s_add_i32 s43, s9, s40
	s_ashr_i32 s9, s69, 31
	v_writelane_b32 v232, s78, 24
	v_and_b32_e32 v2, -16, v2
	v_ashrrev_i32_e32 v4, 6, v3
	s_mul_i32 s9, s72, s9
	s_mul_hi_u32 s40, s72, s69
	v_writelane_b32 v232, s79, 25
	s_ashr_i32 s0, s38, 6
	v_add_u32_e32 v2, v4, v2
	v_lshlrev_b32_e32 v1, 5, v1
	v_and_b32_e32 v4, 3, v4
	s_add_i32 s9, s40, s9
	s_mul_i32 s39, s39, s69
	v_and_b32_e32 v16, 32, v1
	v_and_b32_e32 v1, 0xc0, v3
	v_and_or_b32 v4, v2, s1, v4
	s_ashr_i32 s1, s38, 8
	s_lshl_b64 s[34:35], s[52:53], 8
	s_lshl_b32 s8, s0, 10
	s_add_i32 s9, s9, s39
	s_mul_i32 s39, s72, s69
	v_readlane_b32 s40, v232, 11
	v_sub_u32_e32 v0, v0, v1
	v_lshlrev_b32_e32 v1, 1, v2
	v_lshrrev_b32_e32 v3, 2, v2
	v_readlane_b32 s41, v232, 12
	s_add_u32 s78, s40, s39
	v_ashrrev_i16_sdwa v0, v155, sext(v0) dst_sel:DWORD dst_unused:UNUSED_PAD src0_sel:DWORD src1_sel:BYTE_0
	v_and_b32_e32 v1, 24, v1
	v_and_b32_e32 v3, 4, v3
	s_addc_u32 s79, s41, s9
	s_add_i32 s9, s8, 0
	v_bfe_i32 v17, v0, 0, 16
	v_or3_b32 v1, v4, v3, v1
	s_add_i32 m0, s9, 0x10000
	v_add_u32_e32 v0, v16, v17
	v_mul_lo_u32 v1, v1, s52
	global_load_lds_dwordx4 v96, s[78:79]
	s_add_i32 m0, s9, 0x12000
	v_add_lshl_u32 v134, v1, v0, 1
	s_add_u32 s40, s78, s34
	global_load_lds_dwordx4 v134, s[78:79]
	s_addc_u32 s41, s79, s35
	s_add_i32 m0, s9, 0x14000
	s_mul_i32 s42, s72, s46
	global_load_lds_dwordx4 v96, s[40:41]
	s_add_i32 m0, s9, 0x16000
	v_readlane_b32 s48, v232, 4
	v_readlane_b32 s49, v232, 5
	s_add_u32 s42, s48, s42
	s_addc_u32 s43, s49, s43
	s_add_i32 s98, s9, 0x2000
	v_mul_lo_u32 v18, v2, s52
	global_load_lds_dwordx4 v134, s[40:41]
	s_mov_b32 m0, s9
	s_add_u32 s48, s42, s34
	v_add_lshl_u32 v132, v0, v18, 1
	global_load_lds_dwordx4 v130, s[42:43]
	s_mov_b32 m0, s98
	s_addc_u32 s49, s43, s35
	s_add_i32 s99, s9, 0x4000
	global_load_lds_dwordx4 v132, s[42:43]
	s_mov_b32 m0, s99
	s_add_i32 s76, s9, 0x6000
	global_load_lds_dwordx4 v130, s[48:49]
	s_mov_b32 m0, s76
	v_mov_b32_e32 v135, v97
	global_load_lds_dwordx4 v132, s[48:49]
	s_cmp_eq_u32 s1, 1
	v_lshl_add_u64 v[2:3], s[40:41], 0, v[96:97]
	v_lshl_add_u64 v[0:1], s[40:41], 0, v[134:135]
	v_mov_b32_e32 v131, v97
	v_mov_b32_e32 v133, v97
	s_cselect_b64 s[40:41], -1, 0
	v_lshl_add_u64 v[8:9], s[78:79], 0, v[96:97]
	v_lshl_add_u64 v[4:5], s[78:79], 0, v[134:135]
	v_lshl_add_u64 v[6:7], s[42:43], 0, v[130:131]
	v_writelane_b32 v232, s40, 6
	v_lshl_add_u64 v[10:11], s[42:43], 0, v[132:133]
	v_writelane_b32 v232, s41, 7
	s_add_i32 m0, s9, 0x18000
	v_lshl_add_u64 v[8:9], v[8:9], 0, s[12:13]
	global_load_lds_dwordx4 v[8:9], off
	v_lshl_add_u64 v[4:5], v[4:5], 0, s[12:13]
	s_add_i32 m0, s9, 0x1a000
	s_add_i32 s77, s9, 0x8000
	global_load_lds_dwordx4 v[4:5], off
	v_lshl_add_u64 v[4:5], v[6:7], 0, s[12:13]
	s_mov_b32 m0, s77
	s_add_i32 s86, s9, 0xa000
	global_load_lds_dwordx4 v[4:5], off
	v_lshl_add_u64 v[4:5], v[10:11], 0, s[12:13]
	s_mov_b32 m0, s86
	v_lshl_add_u64 v[2:3], v[2:3], 0, s[12:13]
	global_load_lds_dwordx4 v[4:5], off
	s_add_i32 m0, s9, 0x1c000
	v_lshl_add_u64 v[0:1], v[0:1], 0, s[12:13]
	global_load_lds_dwordx4 v[2:3], off
	s_add_i32 m0, s9, 0x1e000
	s_and_b32 s48, s0, 3
	global_load_lds_dwordx4 v[0:1], off
	s_cmp_lg_u32 s1, 1
	s_cbranch_scc1 .LBB0_323
	s_barrier
.LBB0_323:
	s_waitcnt vmcnt(8)
	s_barrier
	v_bfe_u32 v0, v12, 4, 2
	v_and_b32_e32 v1, 15, v12
	v_lshlrev_b32_e32 v3, 4, v0
	v_lshl_or_b32 v146, s1, 6, v1
	v_lshl_or_b32 v1, v1, 6, v3
	v_lshlrev_b32_e32 v3, 2, v12
	s_lshr_b32 s64, s52, 6
	s_lshl_b32 s0, s1, 13
	v_and_b32_e32 v3, 32, v3
	v_bitop3_b32 v4, v1, s0, v3 bitop3:0xde
	s_lshl_b32 s0, s48, 12
	s_add_i32 s87, s64, -2
	s_cmpk_lt_u32 s38, 0x100
	v_bitop3_b32 v147, v1, s0, v3 bitop3:0xde
	s_cselect_b64 s[0:1], -1, 0
	s_lshl_b32 s65, s50, 2
	v_cvt_f32_u32_e32 v1, s65
	v_lshlrev_b32_e32 v2, 3, v0
	v_writelane_b32 v233, s0, 50
	v_cmp_eq_u32_e64 s[38:39], 0, v0
	v_rcp_iflag_f32_e32 v0, v1
	v_writelane_b32 v233, s1, 51
	s_mov_b32 s0, s54
	s_mov_b32 s1, s47
	s_mov_b64 s[62:63], s[0:1]
	v_readlane_b32 s0, v233, 58
	s_lshr_b32 s61, s54, 3
	v_readlane_b32 s1, v233, 59
	s_and_b64 s[0:1], s[0:1], exec
	v_mul_f32_e32 v0, 0x4f7ffffe, v0
	v_readlane_b32 s0, v232, 2
	v_readlane_b32 s40, v233, 56
	v_cvt_u32_f32_e32 v0, v0
	v_readlane_b32 s1, v232, 3
	v_readlane_b32 s41, v233, 57
	s_cselect_b32 s1, s41, s1
	s_cselect_b32 s0, s40, s0
	v_writelane_b32 v232, s0, 8
	v_mov_b32_e32 v1, v97
	s_waitcnt vmcnt(6)
	s_mov_b32 s66, 0
	v_writelane_b32 v232, s1, 9
	v_readfirstlane_b32 s1, v0
	v_add_u32_e32 v0, v15, v13
	s_sub_i32 s0, 0, s65
	v_add_lshl_u32 v0, v0, v14, 1
	s_mul_i32 s0, s0, s1
	v_lshl_add_u64 v[136:137], s[34:35], 0, v[0:1]
	v_add_u32_e32 v0, v18, v16
	s_mul_hi_u32 s0, s1, s0
	v_add_lshl_u32 v0, v0, v17, 1
	s_mov_b32 s60, s48
	v_lshl_or_b32 v148, s48, 5, v2
	s_add_i32 s68, s1, s0
	v_lshl_add_u64 v[138:139], s[34:35], 0, v[0:1]
	v_add_u32_e32 v149, 0, v4
	s_barrier
	s_mov_b32 s51, 0
	v_writelane_b32 v232, s51, 60
	s_branch .LBB0_326
